# adds: out0/out1 residual epilogues software-pipelined like the Down one
# baseline (speedup 1.0000x reference)
.LBB0_1015:
	s_lshl_b32 s20, s11, 8
	s_min_i32 s18, s11, 0x100
	s_ashr_i32 s21, s18, 5
	s_add_i32 s31, s20, 0xffff0000
	s_cmpk_gt_i32 s11, 0xff
	s_cselect_b32 s11, s31, s20
	v_add_u32_e32 v154, s11, v1
	v_lshl_or_b32 v155, s10, 8, v147
	s_mul_i32 s21, s21, 0x9000
	s_cselect_b32 s19, s37, s49
	s_cselect_b32 s18, s33, s48
	v_lshlrev_b32_e32 v155, 2, v155
	v_lshl_add_u32 v154, v154, 12, v155
	v_add_u32_e32 v155, s21, v155
	v_readlane_b32 s10, v255, 11
	v_readlane_b32 s20, v255, 13
	s_nop 1
	v_add_co_u32_e32 v156, vcc, s10, v155
	v_mov_b32_e32 v157, s20
	s_nop 1
	v_addc_co_u32_e32 v157, vcc, 0, v157, vcc
	global_load_dwordx4 v[130:133], v[156:157], off
	global_load_dwordx4 v[142:145], v154, s[18:19]
	s_add_u32 s10, s18, 0x10000
	s_addc_u32 s11, s19, 0
	global_load_dwordx4 v[150:153], v154, s[10:11]
	s_waitcnt vmcnt(2)
	s_waitcnt vmcnt(1)
	v_pk_fma_f32 v[142:143], v[126:127], v[130:131], v[142:143]
	v_pk_fma_f32 v[144:145], v[128:129], v[132:133], v[144:145]
	global_store_dwordx4 v154, v[142:145], s[18:19]
	s_add_u32 s10, s18, 0x20000
	s_addc_u32 s11, s19, 0
	global_load_dwordx4 v[126:129], v154, s[10:11]
	s_waitcnt vmcnt(2)
	v_pk_fma_f32 v[150:151], v[122:123], v[130:131], v[150:151]
	v_pk_fma_f32 v[152:153], v[124:125], v[132:133], v[152:153]
	s_add_u32 vcc_lo, s18, 0x10000
	s_addc_u32 vcc_hi, s19, 0
	global_store_dwordx4 v154, v[150:153], vcc
	s_add_u32 s10, s18, 0x30000
	s_addc_u32 s11, s19, 0
	global_load_dwordx4 v[142:145], v154, s[10:11]
	s_add_u32 s10, s18, 0x80000
	s_addc_u32 s11, s19, 0
	global_load_dwordx4 v[122:125], v154, s[10:11]
	s_waitcnt vmcnt(3)
	v_pk_fma_f32 v[126:127], v[118:119], v[130:131], v[126:127]
	v_pk_fma_f32 v[128:129], v[120:121], v[132:133], v[128:129]
	s_add_u32 vcc_lo, s18, 0x20000
	s_addc_u32 vcc_hi, s19, 0
	global_store_dwordx4 v154, v[126:129], vcc
	s_add_u32 s10, s18, 0x90000
	s_addc_u32 s11, s19, 0
	global_load_dwordx4 v[150:153], v154, s[10:11]
	s_add_u32 s10, s18, 0xa0000
	s_addc_u32 s11, s19, 0
	global_load_dwordx4 v[118:121], v154, s[10:11]
	s_waitcnt vmcnt(4)
	v_pk_fma_f32 v[142:143], v[114:115], v[130:131], v[142:143]
	v_pk_fma_f32 v[144:145], v[116:117], v[132:133], v[144:145]
	s_add_u32 vcc_lo, s18, 0x30000
	s_addc_u32 vcc_hi, s19, 0
	global_store_dwordx4 v154, v[142:145], vcc
	global_load_dwordx4 v[126:129], v[156:157], off offset:64
	s_add_u32 s10, s18, 0xb0000
	s_addc_u32 s11, s19, 0
	global_load_dwordx4 v[114:117], v154, s[10:11]
	global_load_dwordx4 v[142:145], v154, s[18:19] offset:64
	s_waitcnt vmcnt(7)
	v_pk_fma_f32 v[122:123], v[110:111], v[130:131], v[122:123]
	v_pk_fma_f32 v[124:125], v[112:113], v[132:133], v[124:125]
	s_add_u32 vcc_lo, s18, 0x80000
	s_addc_u32 vcc_hi, s19, 0
	global_store_dwordx4 v154, v[122:125], vcc
	s_add_u32 s10, s18, 0x10000
	s_addc_u32 s11, s19, 0
	global_load_dwordx4 v[110:113], v154, s[10:11] offset:64
	s_add_u32 s10, s18, 0x20000
	s_addc_u32 s11, s19, 0
	global_load_dwordx4 v[122:125], v154, s[10:11] offset:64
	s_waitcnt vmcnt(8)
	v_pk_fma_f32 v[150:151], v[106:107], v[130:131], v[150:151]
	v_pk_fma_f32 v[152:153], v[108:109], v[132:133], v[152:153]
	s_add_u32 vcc_lo, s18, 0x90000
	s_addc_u32 vcc_hi, s19, 0
	global_store_dwordx4 v154, v[150:153], vcc
	s_add_u32 s10, s18, 0x30000
	s_addc_u32 s11, s19, 0
	global_load_dwordx4 v[106:109], v154, s[10:11] offset:64
	s_add_u32 s10, s18, 0x80000
	s_addc_u32 s11, s19, 0
	global_load_dwordx4 v[150:153], v154, s[10:11] offset:64
	s_waitcnt vmcnt(10)
	v_pk_fma_f32 v[118:119], v[102:103], v[130:131], v[118:119]
	v_pk_fma_f32 v[120:121], v[104:105], v[132:133], v[120:121]
	s_add_u32 vcc_lo, s18, 0xa0000
	s_addc_u32 vcc_hi, s19, 0
	global_store_dwordx4 v154, v[118:121], vcc
	s_add_u32 s10, s18, 0x90000
	s_addc_u32 s11, s19, 0
	global_load_dwordx4 v[102:105], v154, s[10:11] offset:64
	s_add_u32 s10, s18, 0xa0000
	s_addc_u32 s11, s19, 0
	global_load_dwordx4 v[118:121], v154, s[10:11] offset:64
	s_waitcnt vmcnt(10)
	v_pk_fma_f32 v[114:115], v[98:99], v[130:131], v[114:115]
	v_pk_fma_f32 v[116:117], v[100:101], v[132:133], v[116:117]
	s_add_u32 vcc_lo, s18, 0xb0000
	s_addc_u32 vcc_hi, s19, 0
	global_store_dwordx4 v154, v[114:117], vcc
	s_add_u32 s10, s18, 0xb0000
	s_addc_u32 s11, s19, 0
	global_load_dwordx4 v[98:101], v154, s[10:11] offset:64
	s_waitcnt vmcnt(13)
	s_waitcnt vmcnt(11)
	v_pk_fma_f32 v[142:143], v[94:95], v[126:127], v[142:143]
	v_pk_fma_f32 v[144:145], v[96:97], v[128:129], v[144:145]
	global_store_dwordx4 v154, v[142:145], s[18:19] offset:64
	global_load_dwordx4 v[114:117], v154, s[18:19] offset:512
	s_waitcnt vmcnt(11)
	v_pk_fma_f32 v[110:111], v[90:91], v[126:127], v[110:111]
	v_pk_fma_f32 v[112:113], v[92:93], v[128:129], v[112:113]
	s_add_u32 vcc_lo, s18, 0x10000
	s_addc_u32 vcc_hi, s19, 0
	global_store_dwordx4 v154, v[110:113], vcc offset:64
	s_add_u32 s10, s18, 0x10000
	s_addc_u32 s11, s19, 0
	global_load_dwordx4 v[130:133], v154, s[10:11] offset:512
	s_waitcnt vmcnt(12)
	v_pk_fma_f32 v[122:123], v[86:87], v[126:127], v[122:123]
	v_pk_fma_f32 v[124:125], v[88:89], v[128:129], v[124:125]
	s_add_u32 vcc_lo, s18, 0x20000
	s_addc_u32 vcc_hi, s19, 0
	global_store_dwordx4 v154, v[122:125], vcc offset:64
	s_add_u32 s10, s18, 0x20000
	s_addc_u32 s11, s19, 0
	global_load_dwordx4 v[94:97], v154, s[10:11] offset:512
	s_waitcnt vmcnt(12)
	v_pk_fma_f32 v[106:107], v[82:83], v[126:127], v[106:107]
	v_pk_fma_f32 v[108:109], v[84:85], v[128:129], v[108:109]
	s_add_u32 vcc_lo, s18, 0x30000
	s_addc_u32 vcc_hi, s19, 0
	global_store_dwordx4 v154, v[106:109], vcc offset:64
	global_load_dwordx4 v[142:145], v[156:157], off offset:512
	s_add_u32 s10, s18, 0x30000
	s_addc_u32 s11, s19, 0
	global_load_dwordx4 v[90:93], v154, s[10:11] offset:512
	s_waitcnt vmcnt(14)
	v_pk_fma_f32 v[150:151], v[78:79], v[126:127], v[150:151]
	v_pk_fma_f32 v[152:153], v[80:81], v[128:129], v[152:153]
	s_add_u32 vcc_lo, s18, 0x80000
	s_addc_u32 vcc_hi, s19, 0
	global_store_dwordx4 v154, v[150:153], vcc offset:64
	s_add_u32 s10, s18, 0x80000
	s_addc_u32 s11, s19, 0
	global_load_dwordx4 v[110:113], v154, s[10:11] offset:512
	s_waitcnt vmcnt(14)
	v_pk_fma_f32 v[102:103], v[74:75], v[126:127], v[102:103]
	v_pk_fma_f32 v[104:105], v[76:77], v[128:129], v[104:105]
	s_add_u32 vcc_lo, s18, 0x90000
	s_addc_u32 vcc_hi, s19, 0
	global_store_dwordx4 v154, v[102:105], vcc offset:64
	s_add_u32 s10, s18, 0x90000
	s_addc_u32 s11, s19, 0
	global_load_dwordx4 v[86:89], v154, s[10:11] offset:512
	s_waitcnt vmcnt(15)
	v_pk_fma_f32 v[118:119], v[70:71], v[126:127], v[118:119]
	v_pk_fma_f32 v[120:121], v[72:73], v[128:129], v[120:121]
	s_add_u32 vcc_lo, s18, 0xa0000
	s_addc_u32 vcc_hi, s19, 0
	global_store_dwordx4 v154, v[118:121], vcc offset:64
	s_add_u32 s10, s18, 0xa0000
	s_addc_u32 s11, s19, 0
	global_load_dwordx4 v[122:125], v154, s[10:11] offset:512
	s_waitcnt vmcnt(15)
	v_pk_fma_f32 v[98:99], v[66:67], v[126:127], v[98:99]
	v_pk_fma_f32 v[100:101], v[68:69], v[128:129], v[100:101]
	s_add_u32 vcc_lo, s18, 0xb0000
	s_addc_u32 vcc_hi, s19, 0
	global_store_dwordx4 v154, v[98:101], vcc offset:64
	s_add_u32 s10, s18, 0xb0000
	s_addc_u32 s11, s19, 0
	global_load_dwordx4 v[82:85], v154, s[10:11] offset:512
	s_waitcnt vmcnt(9)
	s_waitcnt vmcnt(15)
	v_pk_fma_f32 v[114:115], v[62:63], v[142:143], v[114:115]
	v_pk_fma_f32 v[116:117], v[64:65], v[144:145], v[116:117]
	global_store_dwordx4 v154, v[114:117], s[18:19] offset:512
	global_load_dwordx4 v[106:109], v154, s[18:19] offset:576
	s_waitcnt vmcnt(15)
	v_pk_fma_f32 v[130:131], v[58:59], v[142:143], v[130:131]
	v_pk_fma_f32 v[132:133], v[60:61], v[144:145], v[132:133]
	s_add_u32 vcc_lo, s18, 0x10000
	s_addc_u32 vcc_hi, s19, 0
	global_store_dwordx4 v154, v[130:133], vcc offset:512
	s_add_u32 s10, s18, 0x10000
	s_addc_u32 s11, s19, 0
	global_load_dwordx4 v[78:81], v154, s[10:11] offset:576
	s_waitcnt vmcnt(15)
	v_pk_fma_f32 v[94:95], v[54:55], v[142:143], v[94:95]
	v_pk_fma_f32 v[96:97], v[56:57], v[144:145], v[96:97]
	s_add_u32 vcc_lo, s18, 0x20000
	s_addc_u32 vcc_hi, s19, 0
	global_store_dwordx4 v154, v[94:97], vcc offset:512
	s_add_u32 s10, s18, 0x20000
	s_addc_u32 s11, s19, 0
	global_load_dwordx4 v[150:153], v154, s[10:11] offset:576
	s_waitcnt vmcnt(14)
	v_pk_fma_f32 v[90:91], v[50:51], v[142:143], v[90:91]
	v_pk_fma_f32 v[92:93], v[52:53], v[144:145], v[92:93]
	s_add_u32 vcc_lo, s18, 0x30000
	s_addc_u32 vcc_hi, s19, 0
	global_store_dwordx4 v154, v[90:93], vcc offset:512
	global_load_dwordx4 v[74:77], v[156:157], off offset:576
	s_add_u32 s10, s18, 0x30000
	s_addc_u32 s11, s19, 0
	global_load_dwordx4 v[102:105], v154, s[10:11] offset:576
	s_waitcnt vmcnt(15)
	v_pk_fma_f32 v[110:111], v[46:47], v[142:143], v[110:111]
	v_pk_fma_f32 v[112:113], v[48:49], v[144:145], v[112:113]
	s_add_u32 vcc_lo, s18, 0x80000
	s_addc_u32 vcc_hi, s19, 0
	global_store_dwordx4 v154, v[110:113], vcc offset:512
	s_add_u32 s10, s18, 0x80000
	s_addc_u32 s11, s19, 0
	global_load_dwordx4 v[70:73], v154, s[10:11] offset:576
	s_waitcnt vmcnt(15)
	v_pk_fma_f32 v[86:87], v[42:43], v[142:143], v[86:87]
	v_pk_fma_f32 v[88:89], v[44:45], v[144:145], v[88:89]
	s_add_u32 vcc_lo, s18, 0x90000
	s_addc_u32 vcc_hi, s19, 0
	global_store_dwordx4 v154, v[86:89], vcc offset:512
	s_add_u32 s10, s18, 0x90000
	s_addc_u32 s11, s19, 0
	global_load_dwordx4 v[118:121], v154, s[10:11] offset:576
	s_waitcnt vmcnt(15)
	v_pk_fma_f32 v[122:123], v[38:39], v[142:143], v[122:123]
	v_pk_fma_f32 v[124:125], v[40:41], v[144:145], v[124:125]
	s_add_u32 vcc_lo, s18, 0xa0000
	s_addc_u32 vcc_hi, s19, 0
	global_store_dwordx4 v154, v[122:125], vcc offset:512
	s_add_u32 s10, s18, 0xa0000
	s_addc_u32 s11, s19, 0
	global_load_dwordx4 v[66:69], v154, s[10:11] offset:576
	s_waitcnt vmcnt(15)
	v_pk_fma_f32 v[82:83], v[34:35], v[142:143], v[82:83]
	v_pk_fma_f32 v[84:85], v[36:37], v[144:145], v[84:85]
	s_add_u32 vcc_lo, s18, 0xb0000
	s_addc_u32 vcc_hi, s19, 0
	global_store_dwordx4 v154, v[82:85], vcc offset:512
	s_add_u32 s10, s18, 0xb0000
	s_addc_u32 s11, s19, 0
	global_load_dwordx4 v[98:101], v154, s[10:11] offset:576
	s_waitcnt vmcnt(9)
	s_waitcnt vmcnt(15)
	v_pk_fma_f32 v[106:107], v[30:31], v[74:75], v[106:107]
	v_pk_fma_f32 v[108:109], v[32:33], v[76:77], v[108:109]
	global_store_dwordx4 v154, v[106:109], s[18:19] offset:576
	s_waitcnt vmcnt(14)
	v_pk_fma_f32 v[78:79], v[26:27], v[74:75], v[78:79]
	v_pk_fma_f32 v[80:81], v[28:29], v[76:77], v[80:81]
	s_add_u32 vcc_lo, s18, 0x10000
	s_addc_u32 vcc_hi, s19, 0
	global_store_dwordx4 v154, v[78:81], vcc offset:576
	s_waitcnt vmcnt(13)
	v_pk_fma_f32 v[150:151], v[22:23], v[74:75], v[150:151]
	v_pk_fma_f32 v[152:153], v[24:25], v[76:77], v[152:153]
	s_add_u32 vcc_lo, s18, 0x20000
	s_addc_u32 vcc_hi, s19, 0
	global_store_dwordx4 v154, v[150:153], vcc offset:576
	s_waitcnt vmcnt(11)
	v_pk_fma_f32 v[102:103], v[18:19], v[74:75], v[102:103]
	v_pk_fma_f32 v[104:105], v[20:21], v[76:77], v[104:105]
	s_add_u32 vcc_lo, s18, 0x30000
	s_addc_u32 vcc_hi, s19, 0
	global_store_dwordx4 v154, v[102:105], vcc offset:576
	s_waitcnt vmcnt(10)
	v_pk_fma_f32 v[70:71], v[14:15], v[74:75], v[70:71]
	v_pk_fma_f32 v[72:73], v[16:17], v[76:77], v[72:73]
	s_add_u32 vcc_lo, s18, 0x80000
	s_addc_u32 vcc_hi, s19, 0
	global_store_dwordx4 v154, v[70:73], vcc offset:576
	s_waitcnt vmcnt(9)
	v_pk_fma_f32 v[118:119], v[10:11], v[74:75], v[118:119]
	v_pk_fma_f32 v[120:121], v[12:13], v[76:77], v[120:121]
	s_add_u32 vcc_lo, s18, 0x90000
	s_addc_u32 vcc_hi, s19, 0
	global_store_dwordx4 v154, v[118:121], vcc offset:576
	s_waitcnt vmcnt(8)
	v_pk_fma_f32 v[66:67], v[6:7], v[74:75], v[66:67]
	v_pk_fma_f32 v[68:69], v[8:9], v[76:77], v[68:69]
	s_add_u32 vcc_lo, s18, 0xa0000
	s_addc_u32 vcc_hi, s19, 0
	global_store_dwordx4 v154, v[66:69], vcc offset:576
	s_waitcnt vmcnt(7)
	v_pk_fma_f32 v[98:99], v[2:3], v[74:75], v[98:99]
	v_pk_fma_f32 v[100:101], v[4:5], v[76:77], v[100:101]
	s_add_u32 vcc_lo, s18, 0xb0000
	s_addc_u32 vcc_hi, s19, 0
	global_store_dwordx4 v154, v[98:101], vcc offset:576
	s_mov_b64 s[10:11], 0xb0000
	s_mov_b64 s[18:19], -1
	s_and_b64 vcc, exec, s[0:1]
	s_cbranch_vccnz .LBB0_1003
	s_andn2_b64 vcc, exec, s[8:9]
	s_cbranch_vccnz .LBB0_1002
	s_barrier
	s_branch .LBB0_1002
